# attention: waves 4-7 delayed by s_sleep 10 after each tile-pair barrier (stagger MFMA vs softmax)
# baseline (speedup 1.0000x reference)
.LBB0_1043:
	s_add_i32 s33, s48, -3
	s_and_b32 s6, s33, 2
	s_mulk_i32 s6, 0x5c00
	s_add_i32 s18, s6, 0
	v_add_u32_e32 v84, s18, v125
	v_add_u32_e32 v83, s18, v184
	s_waitcnt vmcnt(3)
	ds_write_b128 v84, v[24:27]
	s_and_saveexec_b64 s[50:51], s[40:41]
	ds_write_b128 v83, v[28:31]
	s_or_b64 exec, exec, s[50:51]
	v_lshlrev_b32_e32 v85, 1, v185
	v_add3_u32 v85, s18, v85, v126
	s_waitcnt vmcnt(2)
	ds_write_b128 v85, v[36:39] offset:13312
	s_waitcnt vmcnt(1)
	ds_write_b128 v84, v[40:43] offset:23552
	s_and_saveexec_b64 s[50:51], s[40:41]
	ds_write_b128 v83, v[32:35] offset:23552
	s_or_b64 exec, exec, s[50:51]
	s_cmp_gt_i32 s33, s24
	s_waitcnt vmcnt(0)
	ds_write_b128 v85, v[44:47] offset:36864
	s_waitcnt lgkmcnt(0)
	s_barrier
	v_cmp_lt_u32_e32 vcc, 0xff, v155
	s_cbranch_vccz .Latt_stag1
	s_sleep 10
.Latt_stag1:
	s_cbranch_scc1 .LBB0_1054
	s_add_u32 s52, s48, -1
	s_addc_u32 s53, s49, -1
	v_lshlrev_b64 v[24:25], v118, s[52:53]
	v_lshl_add_u64 v[24:25], v[24:25], 1, v[132:133]
	global_load_dwordx4 v[24:27], v[24:25], off
	s_and_saveexec_b64 s[50:51], s[40:41]
	s_cbranch_execz .LBB0_1050
	v_lshlrev_b64 v[28:29], v124, s[52:53]
	v_lshl_add_u64 v[28:29], v[28:29], 1, v[134:135]
	global_load_dwordx4 v[28:31], v[28:29], off

.LBB0_1065:
	s_add_i32 s33, s46, -3
	s_and_b32 s6, s33, 2
	s_mulk_i32 s6, 0x5c00
	s_add_i32 s18, s6, 0
	v_add_u32_e32 v84, s18, v125
	v_add_u32_e32 v83, s18, v184
	s_waitcnt vmcnt(3)
	ds_write_b128 v84, v[28:31]
	s_and_saveexec_b64 s[48:49], s[40:41]
	ds_write_b128 v83, v[24:27]
	s_or_b64 exec, exec, s[48:49]
	v_lshlrev_b32_e32 v85, 1, v185
	v_add3_u32 v85, s18, v85, v126
	s_waitcnt vmcnt(2)
	ds_write_b128 v85, v[36:39] offset:13312
	s_waitcnt vmcnt(1)
	ds_write_b128 v84, v[40:43] offset:23552
	s_and_saveexec_b64 s[48:49], s[40:41]
	ds_write_b128 v83, v[32:35] offset:23552
	s_or_b64 exec, exec, s[48:49]
	s_cmp_gt_i32 s33, s24
	s_waitcnt vmcnt(0)
	ds_write_b128 v85, v[44:47] offset:36864
	s_waitcnt lgkmcnt(0)
	s_barrier
	v_cmp_lt_u32_e32 vcc, 0xff, v155
	s_cbranch_vccz .Latt_stag0
	s_sleep 10
.Latt_stag0:
	s_cbranch_scc1 .LBB0_1076
	s_add_u32 s50, s46, -1
	s_addc_u32 s51, s47, -1
	v_lshlrev_b64 v[28:29], v118, s[50:51]
	v_lshl_add_u64 v[28:29], v[28:29], 1, v[132:133]
	global_load_dwordx4 v[28:31], v[28:29], off
	s_and_saveexec_b64 s[48:49], s[40:41]
	s_cbranch_execz .LBB0_1072
	v_lshlrev_b64 v[24:25], v124, s[50:51]
	v_lshl_add_u64 v[24:25], v[24:25], 1, v[134:135]
	global_load_dwordx4 v[24:27], v[24:25], off
